# v6 + attention row-max: 16 v_max3 chain instead of 53 canonicalising v_max (same result for finite scores), code after kept 64B-aligned
# speedup vs baseline: 1.0042x; 1.0019x over previous
.LBB0_1426:
	s_barrier
	s_andn2_b64 vcc, exec, s[12:13]
	s_cbranch_vccnz .LBB0_1411
	s_nop 0
	v_max3_f32 v4, v18, v19, v20
	v_max3_f32 v4, v4, v21, v22
	v_max3_f32 v4, v4, v23, v24
	v_max3_f32 v4, v4, v25, v26
	v_max3_f32 v4, v4, v27, v28
	v_max3_f32 v4, v4, v29, v30
	v_max3_f32 v4, v4, v31, v32
	v_max3_f32 v4, v4, v33, v34
	v_max3_f32 v4, v4, v35, v36
	v_max3_f32 v4, v4, v37, v38
	v_max3_f32 v4, v4, v39, v40
	v_max3_f32 v4, v4, v41, v42
	v_max3_f32 v4, v4, v43, v44
	v_max3_f32 v4, v4, v45, v46
	v_max3_f32 v4, v4, v47, v48
	v_max_f32_e32 v4, v4, v49
	v_mov_b32_e32 v5, v4
	s_nop 1
	v_permlane32_swap_b32_e32 v4, v5
	v_max_f32_e32 v5, v5, v5
	v_max_f32_e32 v4, v4, v4
	s_cmp_eq_u32 s64, 0
	s_cselect_b64 s[12:13], -1, 0
	s_cmp_lg_u32 s64, 0
	v_max_f32_e32 v4, v4, v5
	s_cbranch_scc0 .LBB0_1429
	s_mov_b32 s0, 0x41000000
	v_cmp_lt_f32_e32 vcc, s0, v4
	s_cmp_lg_u64 vcc, 0
	s_cselect_b64 s[66:67], -1, 0
	s_cbranch_execz .LBB0_1430
	s_branch .LBB0_1431

.LBB0_1433:
	s_and_b64 vcc, exec, s[28:29]
	s_cbranch_vccz .LBB0_1406
	s_barrier
	s_branch .LBB0_1406
	s_nop 0
	s_nop 0
	s_nop 0
	s_nop 0
	s_nop 0
	s_nop 0
	s_nop 0
	s_nop 0
	s_nop 0
	s_nop 0
	s_nop 0
	s_nop 0
	s_nop 0
	s_nop 0
